# speedup vs baseline: 1.0102x; 1.0004x over previous
; __device__ __forceinline__ float rsq_(float x) { return __builtin_amdgcn_rsqf(x); }
; __device__ __forceinline__ void phase_resid(const Params& p, const float* __restrict__ gpost, float scale, const float* __restrict__ wdt) {
;     ...
;       for (int r = 0; r < 2; ++r) {
;         const long row = row0 + r * (NTOK / 2);
;         float ss = 0.f, d[6] = {0.f, 0.f, 0.f, 0.f, 0.f, 0.f};
; #pragma unroll
;         for (int i = 0; i < 4; ++i) {
;           const int c = i * 256 + lane * 4;
;           const float4 x4 = xv[r][i];
;           ss += x4.x * x4.x + x4.y * x4.y + x4.z * x4.z + x4.w * x4.w;
; #pragma unroll
;           for (int h = 0; h < 6; ++h) {
;             const float4 w4 = *(const float4*)(wdt + h * DM + c);
;             d[h] += x4.x * w4.x + x4.y * w4.y + x4.z * w4.z + x4.w * w4.w;
;           }
;         }
;         ss = wave_sum(ss);
;         const float rsx = rsq_(ss * (1.f / DM) + EPS);
; #pragma unroll
;         for (int h = 0; h < 6; ++h) { const float v = wave_sum(d[h]); if (lane == h) L_dtbuf[row * 8 + h] = v * rsx; }
.LBB0_1059:
	s_or_b64 exec, exec, s[24:25]
	s_and_b64 vcc, exec, s[22:23]
	s_cbranch_vccz .LBB0_1054
	global_load_dwordx4 v[48:51], v[134:135], off
	global_load_dwordx4 v[200:203], v[136:137], off
	global_load_dwordx4 v[204:207], v[138:139], off
	global_load_dwordx4 v[208:211], v[140:141], off
	global_load_dwordx4 v[212:215], v[142:143], off
	global_load_dwordx4 v[216:219], v[144:145], off
	global_load_dwordx4 v[220:223], v[134:135], off offset:1024
	global_load_dwordx4 v[224:227], v[146:147], off
	global_load_dwordx4 v[228:231], v[148:149], off
	global_load_dwordx4 v[232:235], v[150:151], off
	global_load_dwordx4 v[236:239], v[152:153], off
	global_load_dwordx4 v[240:243], v[154:155], off
	global_load_dwordx4 v[244:247], v[134:135], off offset:2048
	ds_swizzle_b32 v181, v180 offset:swizzle(SWAP,1)
	s_waitcnt lgkmcnt(0)
	v_add_f32_e32 v180, v180, v181
	ds_swizzle_b32 v181, v180 offset:swizzle(SWAP,2)
	s_waitcnt lgkmcnt(0)
	v_add_f32_e32 v180, v180, v181
	ds_swizzle_b32 v181, v180 offset:swizzle(SWAP,4)
	s_waitcnt lgkmcnt(0)
	v_add_f32_e32 v180, v180, v181
	ds_swizzle_b32 v181, v180 offset:swizzle(SWAP,8)
	s_waitcnt lgkmcnt(0)
	v_add_f32_e32 v180, v180, v181
	ds_swizzle_b32 v181, v180 offset:swizzle(SWAP,16)
	s_waitcnt lgkmcnt(0)
	v_add_f32_e32 v180, v180, v181
	s_nop 0
	v_readlane_b32 s24, v180, 32
	v_readlane_b32 s8, v180, 0
	s_waitcnt vmcnt(0)
	v_mul_f32_e32 v49, v33, v49
	v_fmac_f32_e32 v49, v32, v48
	v_fmac_f32_e32 v49, v34, v50
	v_fmac_f32_e32 v49, v35, v51
	v_add_f32_e32 v60, 0, v49
	v_mov_b64_e32 v[96:97], v[200:201]
	v_mov_b64_e32 v[98:99], v[202:203]
	v_mov_b64_e32 v[80:81], v[204:205]
	v_mov_b64_e32 v[82:83], v[206:207]
	v_mov_b64_e32 v[68:69], v[208:209]
	v_mov_b64_e32 v[70:71], v[210:211]
	v_mov_b64_e32 v[56:57], v[212:213]
	v_mov_b64_e32 v[58:59], v[214:215]
	v_mov_b64_e32 v[48:49], v[216:217]
	v_mov_b64_e32 v[50:51], v[218:219]
	v_mov_b64_e32 v[52:53], v[220:221]
	v_mov_b64_e32 v[54:55], v[222:223]
	v_mov_b32_e32 v180, s24
	v_add_f32_e32 v180, s8, v180
	v_fmamk_f32 v180, v180, 0x3a800000, v183
	v_rsq_f32_e32 v192, v180
	v_lshlrev_b64 v[180:181], 5, v[128:129]
	v_lshl_add_u64 v[180:181], s[10:11], 0, v[180:181]
	s_waitcnt lgkmcnt(0)
	v_mul_f32_e32 v53, v37, v53
	v_fmac_f32_e32 v53, v36, v52
	v_fmac_f32_e32 v53, v38, v54
	v_fmac_f32_e32 v53, v39, v55
	v_add_f32_e32 v72, v60, v53
	v_mov_b64_e32 v[108:109], v[224:225]
	v_mov_b64_e32 v[110:111], v[226:227]
	v_mov_b64_e32 v[92:93], v[228:229]
	v_mov_b64_e32 v[94:95], v[230:231]
	v_mov_b64_e32 v[76:77], v[232:233]
	v_mov_b64_e32 v[78:79], v[234:235]
	v_mov_b64_e32 v[64:65], v[236:237]
	v_mov_b64_e32 v[66:67], v[238:239]
	v_mov_b64_e32 v[52:53], v[240:241]
	v_mov_b64_e32 v[54:55], v[242:243]
	v_mov_b64_e32 v[60:61], v[244:245]
	v_mov_b64_e32 v[62:63], v[246:247]
	s_waitcnt lgkmcnt(0)
	v_mul_f32_e32 v61, v41, v61
	v_fmac_f32_e32 v61, v40, v60
	v_fmac_f32_e32 v61, v42, v62
	v_fmac_f32_e32 v61, v43, v63
	v_add_f32_e32 v100, v72, v61
	global_load_dwordx4 v[116:119], v[156:157], off
	global_load_dwordx4 v[104:107], v[158:159], off
	global_load_dwordx4 v[88:91], v[160:161], off
	global_load_dwordx4 v[72:75], v[162:163], off
	global_load_dwordx4 v[60:63], v[164:165], off
	global_load_dwordx4 v[84:87], v[134:135], off offset:3072
	global_load_dwordx4 v[200:203], v[166:167], off
	global_load_dwordx4 v[204:207], v[168:169], off
	global_load_dwordx4 v[208:211], v[170:171], off
	global_load_dwordx4 v[212:215], v[174:175], off
	global_load_dwordx4 v[216:219], v[176:177], off
	s_waitcnt vmcnt(0) lgkmcnt(0)
	v_mul_f32_e32 v85, v45, v85
	v_fmac_f32_e32 v85, v44, v84
	v_fmac_f32_e32 v85, v46, v86
	v_fmac_f32_e32 v85, v47, v87
	v_add_f32_e32 v193, v100, v85
	v_mov_b64_e32 v[124:125], v[200:201]
	v_mov_b64_e32 v[126:127], v[202:203]
	v_mov_b64_e32 v[120:121], v[204:205]
	v_mov_b64_e32 v[122:123], v[206:207]
	v_mov_b64_e32 v[112:113], v[208:209]
	v_mov_b64_e32 v[114:115], v[210:211]
	v_mov_b64_e32 v[100:101], v[212:213]
	v_mov_b64_e32 v[102:103], v[214:215]
	v_mov_b64_e32 v[84:85], v[216:217]
	v_mov_b64_e32 v[86:87], v[218:219]
	ds_swizzle_b32 v129, v193 offset:swizzle(SWAP,1)
	s_waitcnt lgkmcnt(0)
	v_add_f32_e32 v129, v193, v129
	ds_swizzle_b32 v193, v129 offset:swizzle(SWAP,2)
	s_waitcnt lgkmcnt(0)
	v_add_f32_e32 v129, v129, v193
	ds_swizzle_b32 v193, v129 offset:swizzle(SWAP,4)
	s_waitcnt lgkmcnt(0)
	v_add_f32_e32 v129, v129, v193
	ds_swizzle_b32 v193, v129 offset:swizzle(SWAP,8)
	s_waitcnt lgkmcnt(0)
	v_add_f32_e32 v129, v129, v193
	ds_swizzle_b32 v193, v129 offset:swizzle(SWAP,16)
	s_waitcnt lgkmcnt(0)
	v_add_f32_e32 v129, v129, v193
	s_nop 0
	v_readlane_b32 s8, v129, 0
	v_readlane_b32 s26, v129, 32
	s_and_saveexec_b64 s[24:25], s[0:1]
	s_cbranch_execz .LBB0_1062
	v_mov_b32_e32 v129, s26
	v_add_f32_e32 v129, s8, v129
	v_mul_f32_e32 v129, v192, v129
	global_store_dword v[180:181], v129, off
.LBB0_1062:
	s_or_b64 exec, exec, s[24:25]
	v_mul_f32_e32 v97, v33, v97
	v_fmac_f32_e32 v97, v32, v96
	v_fmac_f32_e32 v97, v34, v98
	v_fmac_f32_e32 v97, v35, v99
	v_add_f32_e32 v96, 0, v97
	v_mul_f32_e32 v97, v37, v109
	v_fmac_f32_e32 v97, v36, v108
	v_fmac_f32_e32 v97, v38, v110
	v_fmac_f32_e32 v97, v39, v111
	v_add_f32_e32 v96, v96, v97
	v_mul_f32_e32 v97, v41, v117
	v_fmac_f32_e32 v97, v40, v116
	v_fmac_f32_e32 v97, v42, v118
	v_fmac_f32_e32 v97, v43, v119
	v_add_f32_e32 v96, v96, v97
	v_mul_f32_e32 v97, v45, v125
	v_fmac_f32_e32 v97, v44, v124
	v_fmac_f32_e32 v97, v46, v126
	v_fmac_f32_e32 v97, v47, v127
	v_add_f32_e32 v96, v96, v97
	ds_swizzle_b32 v97, v96 offset:swizzle(SWAP,1)
	s_waitcnt lgkmcnt(0)
	v_add_f32_e32 v96, v96, v97
	ds_swizzle_b32 v97, v96 offset:swizzle(SWAP,2)
	s_waitcnt lgkmcnt(0)
	v_add_f32_e32 v96, v96, v97
	ds_swizzle_b32 v97, v96 offset:swizzle(SWAP,4)
	s_waitcnt lgkmcnt(0)
	v_add_f32_e32 v96, v96, v97
	ds_swizzle_b32 v97, v96 offset:swizzle(SWAP,8)
	s_waitcnt lgkmcnt(0)
	v_add_f32_e32 v96, v96, v97
	ds_swizzle_b32 v97, v96 offset:swizzle(SWAP,16)
	s_waitcnt lgkmcnt(0)
	v_add_f32_e32 v96, v96, v97
	s_nop 0
	v_readlane_b32 s8, v96, 0
	v_readlane_b32 s26, v96, 32
	s_and_saveexec_b64 s[24:25], s[2:3]
	s_cbranch_execz .LBB0_1064
	v_mov_b32_e32 v96, s26
	v_add_f32_e32 v96, s8, v96
	v_mul_f32_e32 v96, v192, v96
	global_store_dword v[180:181], v96, off offset:4

; __device__ __forceinline__ float rsq_(float x) { return __builtin_amdgcn_rsqf(x); }
; __device__ __forceinline__ void phase_resid(const Params& p, const float* __restrict__ gpost, float scale, const float* __restrict__ wdt) {
;     ...
;       for (int r = 0; r < 2; ++r) {
;         const long row = row0 + r * (NTOK / 2);
;         float ss = 0.f, d[6] = {0.f, 0.f, 0.f, 0.f, 0.f, 0.f};
; #pragma unroll
;         for (int i = 0; i < 4; ++i) {
;           const int c = i * 256 + lane * 4;
;           const float4 x4 = xv[r][i];
;           ss += x4.x * x4.x + x4.y * x4.y + x4.z * x4.z + x4.w * x4.w;
; #pragma unroll
;           for (int h = 0; h < 6; ++h) {
;             const float4 w4 = *(const float4*)(wdt + h * DM + c);
;             d[h] += x4.x * w4.x + x4.y * w4.y + x4.z * w4.z + x4.w * w4.w;
;           }
;         }
;         ss = wave_sum(ss);
;         const float rsx = rsq_(ss * (1.f / DM) + EPS);
; #pragma unroll
;         for (int h = 0; h < 6; ++h) { const float v = wave_sum(d[h]); if (lane == h) L_dtbuf[row * 8 + h] = v * rsx; }
.LBB0_1072:
	s_or_b64 exec, exec, s[24:25]
	global_load_dwordx4 v[32:35], v[134:135], off
	global_load_dwordx4 v[200:203], v[136:137], off
	global_load_dwordx4 v[204:207], v[138:139], off
	global_load_dwordx4 v[208:211], v[140:141], off
	global_load_dwordx4 v[212:215], v[142:143], off
	global_load_dwordx4 v[216:219], v[144:145], off
	global_load_dwordx4 v[220:223], v[134:135], off offset:1024
	global_load_dwordx4 v[224:227], v[146:147], off
	global_load_dwordx4 v[228:231], v[148:149], off
	global_load_dwordx4 v[232:235], v[150:151], off
	global_load_dwordx4 v[236:239], v[152:153], off
	global_load_dwordx4 v[240:243], v[154:155], off
	global_load_dwordx4 v[244:247], v[134:135], off offset:2048
	ds_swizzle_b32 v112, v191 offset:swizzle(SWAP,1)
	s_waitcnt lgkmcnt(0)
	v_add_f32_e32 v112, v191, v112
	ds_swizzle_b32 v113, v112 offset:swizzle(SWAP,2)
	s_waitcnt lgkmcnt(0)
	v_add_f32_e32 v112, v112, v113
	ds_swizzle_b32 v113, v112 offset:swizzle(SWAP,4)
	s_waitcnt lgkmcnt(0)
	v_add_f32_e32 v112, v112, v113
	ds_swizzle_b32 v113, v112 offset:swizzle(SWAP,8)
	s_waitcnt lgkmcnt(0)
	v_add_f32_e32 v112, v112, v113
	ds_swizzle_b32 v113, v112 offset:swizzle(SWAP,16)
	s_waitcnt lgkmcnt(0)
	v_add_f32_e32 v112, v112, v113
	s_nop 0
	v_readlane_b32 s24, v112, 32
	v_readlane_b32 s8, v112, 0
	s_waitcnt vmcnt(0)
	v_mul_f32_e32 v33, v17, v33
	v_fmac_f32_e32 v33, v16, v32
	v_fmac_f32_e32 v33, v18, v34
	v_fmac_f32_e32 v33, v19, v35
	v_add_f32_e32 v44, 0, v33
	v_mov_b64_e32 v[80:81], v[200:201]
	v_mov_b64_e32 v[82:83], v[202:203]
	v_mov_b64_e32 v[64:65], v[204:205]
	v_mov_b64_e32 v[66:67], v[206:207]
	v_mov_b64_e32 v[52:53], v[208:209]
	v_mov_b64_e32 v[54:55], v[210:211]
	v_mov_b64_e32 v[40:41], v[212:213]
	v_mov_b64_e32 v[42:43], v[214:215]
	v_mov_b64_e32 v[32:33], v[216:217]
	v_mov_b64_e32 v[34:35], v[218:219]
	v_mov_b64_e32 v[36:37], v[220:221]
	v_mov_b64_e32 v[38:39], v[222:223]
	v_mov_b32_e32 v112, s24
	v_add_f32_e32 v112, s8, v112
	v_fmamk_f32 v112, v112, 0x3a800000, v183
	v_rsq_f32_e32 v114, v112
	v_lshlrev_b64 v[112:113], 5, v[178:179]
	v_lshl_add_u64 v[112:113], s[10:11], 0, v[112:113]
	s_waitcnt lgkmcnt(0)
	v_mul_f32_e32 v37, v21, v37
	v_fmac_f32_e32 v37, v20, v36
	v_fmac_f32_e32 v37, v22, v38
	v_fmac_f32_e32 v37, v23, v39
	v_add_f32_e32 v56, v44, v37
	v_mov_b64_e32 v[92:93], v[224:225]
	v_mov_b64_e32 v[94:95], v[226:227]
	v_mov_b64_e32 v[76:77], v[228:229]
	v_mov_b64_e32 v[78:79], v[230:231]
	v_mov_b64_e32 v[60:61], v[232:233]
	v_mov_b64_e32 v[62:63], v[234:235]
	v_mov_b64_e32 v[48:49], v[236:237]
	v_mov_b64_e32 v[50:51], v[238:239]
	v_mov_b64_e32 v[36:37], v[240:241]
	v_mov_b64_e32 v[38:39], v[242:243]
	v_mov_b64_e32 v[44:45], v[244:245]
	v_mov_b64_e32 v[46:47], v[246:247]
	s_waitcnt lgkmcnt(0)
	v_mul_f32_e32 v45, v25, v45
	v_fmac_f32_e32 v45, v24, v44
	v_fmac_f32_e32 v45, v26, v46
	v_fmac_f32_e32 v45, v27, v47
	v_add_f32_e32 v84, v56, v45
	global_load_dwordx4 v[100:103], v[156:157], off
	global_load_dwordx4 v[88:91], v[158:159], off
	global_load_dwordx4 v[72:75], v[160:161], off
	global_load_dwordx4 v[56:59], v[162:163], off
	global_load_dwordx4 v[44:47], v[164:165], off
	global_load_dwordx4 v[68:71], v[134:135], off offset:3072
	global_load_dwordx4 v[200:203], v[166:167], off
	global_load_dwordx4 v[204:207], v[168:169], off
	global_load_dwordx4 v[208:211], v[170:171], off
	global_load_dwordx4 v[212:215], v[174:175], off
	global_load_dwordx4 v[216:219], v[176:177], off
	s_waitcnt vmcnt(0) lgkmcnt(0)
	v_mul_f32_e32 v69, v29, v69
	v_fmac_f32_e32 v69, v28, v68
	v_fmac_f32_e32 v69, v30, v70
	v_fmac_f32_e32 v69, v31, v71
	v_add_f32_e32 v115, v84, v69
	v_mov_b64_e32 v[108:109], v[200:201]
	v_mov_b64_e32 v[110:111], v[202:203]
	v_mov_b64_e32 v[104:105], v[204:205]
	v_mov_b64_e32 v[106:107], v[206:207]
	v_mov_b64_e32 v[96:97], v[208:209]
	v_mov_b64_e32 v[98:99], v[210:211]
	v_mov_b64_e32 v[84:85], v[212:213]
	v_mov_b64_e32 v[86:87], v[214:215]
	v_mov_b64_e32 v[68:69], v[216:217]
	v_mov_b64_e32 v[70:71], v[218:219]
	ds_swizzle_b32 v116, v115 offset:swizzle(SWAP,1)
	s_waitcnt lgkmcnt(0)
	v_add_f32_e32 v115, v115, v116
	ds_swizzle_b32 v116, v115 offset:swizzle(SWAP,2)
	s_waitcnt lgkmcnt(0)
	v_add_f32_e32 v115, v115, v116
	ds_swizzle_b32 v116, v115 offset:swizzle(SWAP,4)
	s_waitcnt lgkmcnt(0)
	v_add_f32_e32 v115, v115, v116
	ds_swizzle_b32 v116, v115 offset:swizzle(SWAP,8)
	s_waitcnt lgkmcnt(0)
	v_add_f32_e32 v115, v115, v116
	ds_swizzle_b32 v116, v115 offset:swizzle(SWAP,16)
	s_waitcnt lgkmcnt(0)
	v_add_f32_e32 v115, v115, v116
	s_nop 0
	v_readlane_b32 s8, v115, 0
	v_readlane_b32 s26, v115, 32
	s_and_saveexec_b64 s[24:25], s[0:1]
	s_cbranch_execz .LBB0_1074
	v_mov_b32_e32 v115, s26
	v_add_f32_e32 v115, s8, v115
	v_mul_f32_e32 v115, v114, v115
	global_store_dword v[112:113], v115, off
.LBB0_1074:
	s_or_b64 exec, exec, s[24:25]
	v_mul_f32_e32 v81, v17, v81
	v_fmac_f32_e32 v81, v16, v80
	v_fmac_f32_e32 v81, v18, v82
	v_fmac_f32_e32 v81, v19, v83
	v_add_f32_e32 v80, 0, v81
	v_mul_f32_e32 v81, v21, v93
	v_fmac_f32_e32 v81, v20, v92
	v_fmac_f32_e32 v81, v22, v94
	v_fmac_f32_e32 v81, v23, v95
	v_add_f32_e32 v80, v80, v81
	v_mul_f32_e32 v81, v25, v101
	v_fmac_f32_e32 v81, v24, v100
	v_fmac_f32_e32 v81, v26, v102
	v_fmac_f32_e32 v81, v27, v103
	v_add_f32_e32 v80, v80, v81
	v_mul_f32_e32 v81, v29, v109
	v_fmac_f32_e32 v81, v28, v108
	v_fmac_f32_e32 v81, v30, v110
	v_fmac_f32_e32 v81, v31, v111
	v_add_f32_e32 v80, v80, v81
	ds_swizzle_b32 v81, v80 offset:swizzle(SWAP,1)
	s_waitcnt lgkmcnt(0)
	v_add_f32_e32 v80, v80, v81
	ds_swizzle_b32 v81, v80 offset:swizzle(SWAP,2)
	s_waitcnt lgkmcnt(0)
	v_add_f32_e32 v80, v80, v81
	ds_swizzle_b32 v81, v80 offset:swizzle(SWAP,4)
	s_waitcnt lgkmcnt(0)
	v_add_f32_e32 v80, v80, v81
	ds_swizzle_b32 v81, v80 offset:swizzle(SWAP,8)
	s_waitcnt lgkmcnt(0)
	v_add_f32_e32 v80, v80, v81
	ds_swizzle_b32 v81, v80 offset:swizzle(SWAP,16)
	s_waitcnt lgkmcnt(0)
	v_add_f32_e32 v80, v80, v81
	s_nop 0
	v_readlane_b32 s8, v80, 0
	v_readlane_b32 s26, v80, 32
	s_and_saveexec_b64 s[24:25], s[2:3]
	s_cbranch_execz .LBB0_1076
	v_mov_b32_e32 v80, s26
	v_add_f32_e32 v80, s8, v80
	v_mul_f32_e32 v80, v114, v80
	global_store_dword v[112:113], v80, off offset:4
